# MLA attention: waves 4-7 take the per-tile barrier mid-tile (after running-max/rescale), waves 0-3 at tile end; 4-slot LDS ring
# speedup vs baseline: 1.0165x; 1.0165x over previous
; #define MLA_DMA(t, slot) do { _Pragma("unroll") for (int i_ = 0; i_ < 4; ++i_) { const bf16_t* src_ = (pisk[i_] ? kbase : vbase) + poff[i_] + (size_t)(t) * pstep[i_]; \
;         __builtin_amdgcn_global_load_lds((const unsigned*)src_, (LAS unsigned*)(lds + (slot) * SLOT + (w + 8 * i_) * 1024), 16, 0, 0); } } while (0)
; DI void mla_attn_phase(LAS unsigned char* lds, const bf16_t* Qg, const bf16_t* Kg, const bf16_t* Vtg, bf16_t* MIX) {
;     ...
;             for (int kt = 0; kt < NT; ++kt) {
;                 const int sl2 = sl == 0 ? 2 : sl - 1;
;                 if (kt + 2 < NT) MLA_DMA(kt + 2, sl2);
.LBB0_359:
	s_add_i32 s28, s42, 2
	s_cmp_ge_i32 s28, s38
	s_cselect_b64 s[28:29], -1, 0
	s_and_b64 vcc, exec, s[28:29]
	s_cbranch_vccnz .LBB0_361
	s_add_i32 s30, s41, 2
	s_and_b32 s30, s30, 3
	s_lshl_b32 s30, s30, 15
	s_add_i32 s30, s35, s30
	s_mov_b32 m0, s30
	s_nop 0
	global_load_lds_dwordx4 v[210:211], off
	s_add_i32 m0, s30, 0x2000
	s_nop 0
	global_load_lds_dwordx4 v[212:213], off
	s_add_i32 m0, s30, 0x4000
	s_nop 0
	global_load_lds_dwordx4 v[214:215], off
	s_add_i32 m0, s30, 0x6000
	s_nop 0
	global_load_lds_dwordx4 v[216:217], off

; DI void mla_attn_phase(LAS unsigned char* lds, const bf16_t* Qg, const bf16_t* Kg, const bf16_t* Vtg, bf16_t* MIX) {
;     ...
;                 if (kt + 2 < NT) asm volatile("s_waitcnt vmcnt(4) lgkmcnt(0)" ::: "memory"); else asm volatile("s_waitcnt vmcnt(0) lgkmcnt(0)" ::: "memory");
;                 __builtin_amdgcn_s_barrier(); asm volatile("" ::: "memory");
.Lmla_mid:
	s_cmp_lt_u32 s34, 0x80
	s_cbranch_scc1 .Lmla_mid_done
	s_and_b64 vcc, exec, s[28:29]
	s_cbranch_vccnz .Lmla_mid_w0
	s_waitcnt vmcnt(4)
	s_branch .Lmla_mid_bar

; DI unsigned pk2(float lo, float hi) { const f32x2_t v = {lo, hi}; const bf16x2_t b = __builtin_convertvector(v, bf16x2_t); return __builtin_bit_cast(unsigned, b); }
; DI void mla_attn_phase(LAS unsigned char* lds, const bf16_t* Qg, const bf16_t* Kg, const bf16_t* Vtg, bf16_t* MIX) {
;     ...
;                     const float m_new = fmaxf(m_run, mx), alpha = __builtin_amdgcn_exp2f(m_run - m_new); m_run = m_new;
;                     float sum = 0.f;
; #pragma unroll
;                     for (int i = 0; i < 16; ++i) { s0[i] = __builtin_amdgcn_exp2f(s0[i] - m_new); s1[i] = __builtin_amdgcn_exp2f(s1[i] - m_new); sum += s0[i] + s1[i]; }
;                     l_run = l_run * alpha + sum;
;                     if (__any(alpha != 1.f)) {
; #pragma unroll
;                         for (int mt = 0; mt < 4; ++mt)
; #pragma unroll
;                             for (int i = 0; i < 16; ++i) o[mt][i] *= alpha; }
;                     bf16x8 pf[4];
; #pragma unroll
;                     for (int sp = 0; sp < 2; ++sp) { u32x4 p0, p1;
; #pragma unroll
;                         for (int j = 0; j < 4; ++j) { p0[j] = pk2(s0[8 * sp + 2 * j], s0[8 * sp + 2 * j + 1]); p1[j] = pk2(s1[8 * sp + 2 * j], s1[8 * sp + 2 * j + 1]); }
;                         pf[sp] = __builtin_bit_cast(bf16x8, p0); pf[2 + sp] = __builtin_bit_cast(bf16x8, p1); }
;                     __builtin_amdgcn_sched_barrier(0);
;                     MLA_PV();
.Lmla_mid_bar:
	s_barrier
.Lmla_mid_done:
	s_cmp_gt_i32 s40, s39
	s_cbranch_scc1 .LBB0_367
	v_sub_f32_e32 v80, v80, v3
	v_sub_f32_e32 v96, v96, v3
	v_exp_f32_e32 v80, v80
	v_exp_f32_e32 v96, v96
	v_sub_f32_e32 v81, v81, v3
	v_sub_f32_e32 v97, v97, v3
	v_exp_f32_e32 v81, v81
	v_exp_f32_e32 v97, v97
	v_sub_f32_e32 v82, v82, v3
	v_sub_f32_e32 v98, v98, v3
	v_exp_f32_e32 v82, v82
	v_exp_f32_e32 v98, v98
	v_sub_f32_e32 v83, v83, v3
	v_sub_f32_e32 v99, v99, v3
	v_exp_f32_e32 v83, v83
	v_exp_f32_e32 v99, v99
	v_add_f32_e32 v218, v80, v96
	v_sub_f32_e32 v84, v84, v3
	v_add_f32_e32 v218, 0, v218
	v_add_f32_e32 v219, v81, v97
	v_exp_f32_e32 v226, v84
	v_sub_f32_e32 v84, v100, v3
	v_add_f32_e32 v218, v219, v218
	v_add_f32_e32 v219, v82, v98
	v_exp_f32_e32 v100, v84
	v_sub_f32_e32 v84, v85, v3
	v_add_f32_e32 v218, v219, v218
	v_add_f32_e32 v219, v83, v99
	v_exp_f32_e32 v227, v84
	v_sub_f32_e32 v84, v101, v3
	v_sub_f32_e32 v86, v86, v3
	v_exp_f32_e32 v101, v84
	v_add_f32_e32 v84, v219, v218
	v_exp_f32_e32 v218, v86
	v_sub_f32_e32 v86, v102, v3
	v_exp_f32_e32 v102, v86
	v_sub_f32_e32 v86, v87, v3
	v_exp_f32_e32 v87, v86
	v_sub_f32_e32 v86, v103, v3
	v_exp_f32_e32 v103, v86
	v_sub_f32_e32 v86, v88, v3
	v_exp_f32_e32 v88, v86
	v_sub_f32_e32 v86, v104, v3
	v_exp_f32_e32 v104, v86
	v_sub_f32_e32 v86, v89, v3
	v_exp_f32_e32 v89, v86
	v_sub_f32_e32 v86, v105, v3
	v_exp_f32_e32 v105, v86
	v_sub_f32_e32 v86, v90, v3
	v_exp_f32_e32 v90, v86
	v_sub_f32_e32 v86, v106, v3
	v_exp_f32_e32 v106, v86
	v_sub_f32_e32 v86, v91, v3
	v_exp_f32_e32 v91, v86
	v_sub_f32_e32 v86, v107, v3
	v_exp_f32_e32 v107, v86
	v_sub_f32_e32 v86, v92, v3
	v_add_f32_e32 v85, v226, v100
	v_exp_f32_e32 v219, v86
	v_sub_f32_e32 v86, v108, v3
	v_add_f32_e32 v84, v85, v84
	v_add_f32_e32 v85, v227, v101
	v_exp_f32_e32 v108, v86
	v_sub_f32_e32 v86, v93, v3
	v_add_f32_e32 v84, v85, v84
	v_add_f32_e32 v85, v218, v102
	v_exp_f32_e32 v234, v86
	v_sub_f32_e32 v86, v109, v3
	v_add_f32_e32 v84, v85, v84
	v_add_f32_e32 v85, v87, v103
	v_exp_f32_e32 v109, v86
	v_sub_f32_e32 v86, v94, v3
	v_add_f32_e32 v84, v85, v84
	v_add_f32_e32 v85, v88, v104
	v_exp_f32_e32 v235, v86
	v_sub_f32_e32 v86, v110, v3
	v_add_f32_e32 v84, v85, v84
	v_add_f32_e32 v85, v89, v105
	v_exp_f32_e32 v110, v86
	v_sub_f32_e32 v86, v95, v3
	v_add_f32_e32 v84, v85, v84
	v_add_f32_e32 v85, v90, v106
	v_exp_f32_e32 v95, v86
	v_sub_f32_e32 v86, v111, v3
	v_add_f32_e32 v84, v85, v84
	v_add_f32_e32 v85, v91, v107
	v_exp_f32_e32 v111, v86
	v_add_f32_e32 v84, v85, v84
	v_add_f32_e32 v85, v219, v108
	v_add_f32_e32 v84, v85, v84
	v_add_f32_e32 v85, v234, v109
	v_add_f32_e32 v84, v85, v84
	v_add_f32_e32 v85, v235, v110
	v_add_f32_e32 v84, v85, v84
	v_add_f32_e32 v85, v95, v111
	v_add_f32_e32 v236, v85, v84
	v_fmac_f32_e32 v236, v233, v0
	v_cvt_pk_bf16_f32 v80, v80, v81
	v_cvt_pk_bf16_f32 v84, v96, v97
	v_cvt_pk_bf16_f32 v81, v82, v83
	v_cvt_pk_bf16_f32 v85, v98, v99
	v_cvt_pk_bf16_f32 v82, v226, v227
	v_cvt_pk_bf16_f32 v86, v100, v101
	v_cvt_pk_bf16_f32 v83, v218, v87
	v_cvt_pk_bf16_f32 v87, v102, v103
	v_cvt_pk_bf16_f32 v88, v88, v89
	v_cvt_pk_bf16_f32 v92, v104, v105
	v_cvt_pk_bf16_f32 v89, v90, v91
	v_cvt_pk_bf16_f32 v93, v106, v107
	v_cvt_pk_bf16_f32 v90, v219, v234
	v_cvt_pk_bf16_f32 v94, v108, v109
	v_cvt_pk_bf16_f32 v91, v235, v95
	v_cvt_pk_bf16_f32 v95, v110, v111
	v_mfma_f32_32x32x16_bf16 v[64:79], v[144:147], v[80:83], v[64:79]
	v_mfma_f32_32x32x16_bf16 v[48:63], v[140:143], v[80:83], v[48:63]
	s_waitcnt lgkmcnt(0)
	v_mfma_f32_32x32x16_bf16 v[32:47], v[148:151], v[80:83], v[32:47]
	v_mfma_f32_32x32x16_bf16 v[16:31], v[152:155], v[80:83], v[16:31]
	ds_read_b128 v[80:83], v1 offset:13376
	ds_read_b128 v[96:99], v1 offset:17984
	ds_read_b128 v[100:103], v1 offset:22592
	ds_read_b128 v[104:107], v1 offset:27200
	v_mfma_f32_32x32x16_bf16 v[64:79], v[136:139], v[88:91], v[64:79]
	v_mfma_f32_32x32x16_bf16 v[48:63], v[12:15], v[88:91], v[48:63]
	v_mfma_f32_32x32x16_bf16 v[32:47], v[4:7], v[88:91], v[32:47]
	v_mfma_f32_32x32x16_bf16 v[16:31], v[8:11], v[88:91], v[16:31]
	ds_read_b128 v[4:7], v1 offset:13408
	ds_read_b128 v[8:11], v1 offset:18016
	ds_read_b128 v[12:15], v1 offset:22624
	ds_read_b128 v[88:91], v1 offset:27232
	s_waitcnt lgkmcnt(0)
	v_mfma_f32_32x32x16_bf16 v[64:79], v[80:83], v[84:87], v[64:79]
	v_mov_b32_e32 v233, v236
	v_mfma_f32_32x32x16_bf16 v[48:63], v[96:99], v[84:87], v[48:63]
	v_mfma_f32_32x32x16_bf16 v[32:47], v[100:103], v[84:87], v[32:47]
	v_mfma_f32_32x32x16_bf16 v[16:31], v[104:107], v[84:87], v[16:31]
	v_mfma_f32_32x32x16_bf16 v[64:79], v[4:7], v[92:95], v[64:79]
	v_mfma_f32_32x32x16_bf16 v[48:63], v[8:11], v[92:95], v[48:63]
	v_mfma_f32_32x32x16_bf16 v[32:47], v[12:15], v[92:95], v[32:47]
	v_mfma_f32_32x32x16_bf16 v[16:31], v[88:91], v[92:95], v[16:31]
	s_branch .Lmla_tail

; DI void mla_attn_phase(LAS unsigned char* lds, const bf16_t* Qg, const bf16_t* Kg, const bf16_t* Vtg, bf16_t* MIX) {
;     ...
;                 if (kt + 2 < NT) asm volatile("s_waitcnt vmcnt(4) lgkmcnt(0)" ::: "memory"); else asm volatile("s_waitcnt vmcnt(0) lgkmcnt(0)" ::: "memory");
;                 __builtin_amdgcn_s_barrier(); asm volatile("" ::: "memory");
.Lmla_tail:
	s_cmp_lt_u32 s34, 0x80
	s_cbranch_scc0 .LBB0_371
	s_and_b64 vcc, exec, s[28:29]
	s_cbranch_vccnz .Lmla_end_w0
	s_waitcnt vmcnt(4) lgkmcnt(0)
	s_branch .Lmla_end_bar

; DI void mla_attn_phase(LAS unsigned char* lds, const bf16_t* Qg, const bf16_t* Kg, const bf16_t* Vtg, bf16_t* MIX) {
;     ...
;             for (int kt = 0; kt < NT; ++kt) {
;     ...
;                 sl = sl == 2 ? 0 : sl + 1;
.LBB0_371:
	s_add_i32 s41, s41, 1
	s_and_b32 s41, s41, 3
	s_add_i32 s42, s42, 1
	s_add_i32 s40, s40, 64
	v_lshl_add_u64 v[216:217], v[216:217], 0, s[18:19]
	v_lshl_add_u64 v[214:215], v[214:215], 0, s[20:21]
	v_lshl_add_u64 v[212:213], v[212:213], 0, s[2:3]
	s_cmp_eq_u32 s38, s42
	v_lshl_add_u64 v[210:211], v[210:211], 0, s[22:23]
	s_cbranch_scc1 .LBB0_356
	v_mov_b32_e32 v234, v3
	s_branch .LBB0_359
